# final_norm: all loads of a row issued up front (was 2-3 chained round trips per row), gain vector loaded once
# speedup vs baseline: 1.0050x; 1.0044x over previous
.LBB0_3402:
	s_cmp_lt_i32 s42, 25
	s_cselect_b64 s[0:1], -1, 0
	s_cmp_gt_i32 s43, 24
	s_cselect_b64 s[2:3], -1, 0
	s_and_b64 s[0:1], s[0:1], s[2:3]
	s_andn2_b64 vcc, exec, s[0:1]
	s_cbranch_vccnz .LBB0_3460
	v_mbcnt_hi_u32_b32 v0, -1, v210
	v_add_u32_e32 v0, s91, v0
	s_waitcnt lgkmcnt(0)
	s_load_dword s10, s[88:89], 0x160
	s_add_u32 s4, s88, 0x160
	v_readfirstlane_b32 s1, v0
	s_addc_u32 s5, s89, 0
	s_ashr_i32 s1, s1, 6
	s_waitcnt lgkmcnt(0)
	s_mov_b32 s0, s10
	s_lshl_b32 s2, s90, 3
	s_add_i32 s11, s1, s2
	s_cmpk_gt_i32 s11, 0x3fff
	s_cbranch_scc1 .LBB0_3406
	s_load_dwordx4 s[12:15], s[88:89], 0x140
	s_load_dwordx2 s[6:7], s[88:89], 0x150
	s_lshl_b32 s0, s0, 3
	s_ashr_i32 s3, s1, 31
	s_ashr_i32 s9, s2, 31
	s_add_u32 s8, s1, s2
	s_addc_u32 s9, s3, s9
	s_lshl_b64 s[2:3], s[8:9], 6
	s_waitcnt lgkmcnt(0)
	s_add_u32 s1, s6, s2
	s_addc_u32 s3, s7, s3
	s_add_u32 s2, s1, 0x100000
	s_addc_u32 s3, s3, 0
	s_ashr_i32 s1, s0, 31
	s_lshl_b64 s[6:7], s[0:1], 6
	s_lshl_b64 s[8:9], s[8:9], 12
	v_and_b32_e32 v0, 63, v0
	s_add_u32 s8, s14, s8
	v_lshlrev_b32_e32 v0, 4, v0
	v_mov_b32_e32 v1, 0
	s_addc_u32 s9, s15, s9
	v_lshl_add_u64 v[4:5], s[8:9], 0, v[0:1]
	s_mov_b64 s[8:9], 0x800
	v_lshl_add_u64 v[2:3], s[12:13], 0, v[0:1]
	v_lshl_add_u64 v[4:5], v[4:5], 0, s[8:9]
	s_lshl_b64 s[8:9], s[0:1], 12
	v_mov_b32_e32 v0, 0x358637bd
	s_mov_b32 s1, 0x800000
	global_load_dwordx4 v[48:51], v[2:3], off
	global_load_dwordx4 v[52:55], v[2:3], off offset:1024
	global_load_dwordx4 v[56:59], v[2:3], off offset:2048
	global_load_dwordx4 v[60:63], v[2:3], off offset:3072
.LBB0_3405:
	global_load_dwordx4 v[6:9], v1, s[2:3]
	global_load_dwordx4 v[10:13], v1, s[2:3] offset:16
	global_load_dwordx4 v[14:17], v1, s[2:3] offset:32
	global_load_dwordx4 v[18:21], v1, s[2:3] offset:48
	global_load_dwordx4 v[22:25], v[4:5], off offset:-2048
	global_load_dwordx4 v[30:33], v[4:5], off offset:-1024
	global_load_dwordx4 v[40:43], v[4:5], off
	global_load_dwordx4 v[44:47], v[4:5], off offset:1024
	s_add_i32 s11, s11, s0
	s_add_u32 s2, s2, s6
	s_addc_u32 s3, s3, s7
	s_cmpk_lt_i32 s11, 0x4000
	s_waitcnt vmcnt(7)
	v_mov_b32_e32 v34, v7
	v_mov_b32_e32 v35, v8
	v_mov_b32_e32 v7, v9
	s_waitcnt vmcnt(6)
	v_mov_b32_e32 v8, v11
	v_mov_b32_e32 v9, v12
	v_mov_b32_e32 v11, v13
	v_pk_add_f32 v[6:7], v[34:35], v[6:7]
	v_pk_add_f32 v[8:9], v[8:9], v[10:11]
	v_pk_add_f32 v[6:7], v[6:7], v[6:7] op_sel:[0,1] op_sel_hi:[1,0]
	v_pk_add_f32 v[8:9], v[8:9], v[8:9] op_sel:[0,1] op_sel_hi:[1,0]
	s_waitcnt vmcnt(5)
	v_add_f32_e32 v12, v14, v15
	v_add_f32_e32 v14, v16, v17
	s_waitcnt vmcnt(4)
	v_mov_b32_e32 v13, v20
	v_mov_b32_e32 v15, v21
	v_mov_b32_e32 v7, v18
	v_mov_b32_e32 v9, v19
	v_pk_add_f32 v[10:11], v[12:13], v[14:15]
	v_pk_add_f32 v[6:7], v[6:7], v[8:9]
	s_nop 0
	v_pk_add_f32 v[6:7], v[6:7], v[10:11]
	s_nop 0
	v_add_f32_e32 v6, v6, v7
	v_fmamk_f32 v6, v6, 0x3a800000, v0
	v_mul_f32_e32 v7, 0x4b800000, v6
	v_cmp_gt_f32_e32 vcc, s1, v6
	s_nop 1
	v_cndmask_b32_e32 v6, v6, v7, vcc
	v_rsq_f32_e32 v6, v6
	s_nop 0
	v_mul_f32_e32 v7, 0x45800000, v6
	v_cndmask_b32_e32 v18, v6, v7, vcc
	s_waitcnt vmcnt(3)
	v_pk_mul_f32 v[64:65], v[22:23], v[18:19] op_sel_hi:[1,0]
	v_pk_mul_f32 v[66:67], v[24:25], v[18:19] op_sel_hi:[1,0]
	v_pk_mul_f32 v[64:65], v[48:49], v[64:65]
	v_pk_mul_f32 v[66:67], v[50:51], v[66:67]
	global_store_dwordx4 v[4:5], v[64:67], off offset:-2048
	s_waitcnt vmcnt(3)
	v_pk_mul_f32 v[68:69], v[30:31], v[18:19] op_sel_hi:[1,0]
	v_pk_mul_f32 v[70:71], v[32:33], v[18:19] op_sel_hi:[1,0]
	v_pk_mul_f32 v[68:69], v[52:53], v[68:69]
	v_pk_mul_f32 v[70:71], v[54:55], v[70:71]
	global_store_dwordx4 v[4:5], v[68:71], off offset:-1024
	s_waitcnt vmcnt(3)
	v_pk_mul_f32 v[72:73], v[40:41], v[18:19] op_sel_hi:[1,0]
	v_pk_mul_f32 v[74:75], v[42:43], v[18:19] op_sel_hi:[1,0]
	v_pk_mul_f32 v[72:73], v[56:57], v[72:73]
	v_pk_mul_f32 v[74:75], v[58:59], v[74:75]
	global_store_dwordx4 v[4:5], v[72:75], off
	s_waitcnt vmcnt(3)
	v_pk_mul_f32 v[76:77], v[44:45], v[18:19] op_sel_hi:[1,0]
	v_pk_mul_f32 v[78:79], v[46:47], v[18:19] op_sel_hi:[1,0]
	v_pk_mul_f32 v[76:77], v[60:61], v[76:77]
	v_pk_mul_f32 v[78:79], v[62:63], v[78:79]
	global_store_dwordx4 v[4:5], v[76:79], off offset:1024
	v_lshl_add_u64 v[4:5], v[4:5], 0, s[8:9]
	s_cbranch_scc1 .LBB0_3405
